# v11 + start-up census poll reads its 16 counters with all loads in flight
# baseline (speedup 1.0000x reference)
; __device__ __forceinline__ unsigned xb_ld(unsigned* p)              { return __hip_atomic_load(p, __ATOMIC_RELAXED, __HIP_MEMORY_SCOPE_AGENT); }
; __device__ __forceinline__ void xcd_barrier_complete(unsigned* bar, unsigned x, unsigned& nloc, unsigned& nx) {
;     ...
;     for (;;) {
;         sum = 0u; cnt = 0u; mine = 0u;
; #pragma unroll
;         for (unsigned j = 0; j < 16; ++j) { const unsigned c = xb_ld(&bar[XB_XCNT(j)]); sum += c; cnt += (c > 0u) ? 1u : 0u; mine = (j == x) ? c : mine; }
;         if (sum == G) break;
;         __builtin_amdgcn_s_sleep(1);
;         if ((++sp & 255u) == 0u) { if (xb_ld(&bar[XB_TMO])) break; if (sp > XB_SPIN_CAP) { atomicAdd(&bar[XB_TMO], 1u); break; } }
;     }
.LBB0_20:
	v_readlane_b32 s2, v251, 9
	v_readlane_b32 s3, v251, 10
	s_mov_b64 s[4:5], -1
	s_waitcnt lgkmcnt(0)
	s_nop 4
	global_load_dword v0, v147, s[2:3] sc1
	v_readlane_b32 s2, v251, 11
	v_readlane_b32 s3, v251, 12
	s_nop 4
	global_load_dword v1, v147, s[2:3] sc1
	v_readlane_b32 s2, v251, 13
	v_readlane_b32 s3, v251, 14
	s_nop 4
	global_load_dword v2, v147, s[2:3] sc1
	v_readlane_b32 s2, v251, 15
	v_readlane_b32 s3, v251, 16
	s_nop 4
	global_load_dword v3, v147, s[2:3] sc1
	v_readlane_b32 s2, v251, 17
	v_readlane_b32 s3, v251, 18
	s_nop 4
	global_load_dword v4, v147, s[2:3] sc1
	v_readlane_b32 s2, v251, 19
	v_readlane_b32 s3, v251, 20
	s_nop 4
	global_load_dword v5, v147, s[2:3] sc1
	v_readlane_b32 s2, v251, 21
	v_readlane_b32 s3, v251, 22
	s_nop 4
	global_load_dword v6, v147, s[2:3] sc1
	v_readlane_b32 s2, v251, 23
	v_readlane_b32 s3, v251, 24
	s_nop 4
	global_load_dword v7, v147, s[2:3] sc1
	v_readlane_b32 s2, v251, 25
	v_readlane_b32 s3, v251, 26
	s_nop 4
	global_load_dword v8, v147, s[2:3] sc1
	v_readlane_b32 s2, v251, 27
	v_readlane_b32 s3, v251, 28
	s_nop 4
	global_load_dword v9, v147, s[2:3] sc1
	v_readlane_b32 s2, v251, 29
	v_readlane_b32 s3, v251, 30
	s_nop 4
	global_load_dword v10, v147, s[2:3] sc1
	v_readlane_b32 s2, v251, 31
	v_readlane_b32 s3, v251, 32
	s_nop 4
	global_load_dword v11, v147, s[2:3] sc1
	v_readlane_b32 s2, v251, 33
	v_readlane_b32 s3, v251, 34
	s_nop 4
	global_load_dword v12, v147, s[2:3] sc1
	v_readlane_b32 s2, v251, 35
	v_readlane_b32 s3, v251, 36
	s_nop 4
	global_load_dword v13, v147, s[2:3] sc1
	v_readlane_b32 s2, v251, 37
	v_readlane_b32 s3, v251, 38
	s_nop 4
	global_load_dword v14, v147, s[2:3] sc1
	v_readlane_b32 s2, v251, 39
	v_readlane_b32 s3, v251, 40
	s_nop 4
	global_load_dword v15, v147, s[2:3] sc1
	s_mov_b64 s[2:3], -1
	s_waitcnt vmcnt(0)
	v_add_u32_e32 v16, v1, v0
	v_add_u32_e32 v16, v16, v2
	v_add_u32_e32 v16, v16, v3
	v_add_u32_e32 v16, v16, v4
	v_add_u32_e32 v16, v16, v5
	v_add_u32_e32 v16, v16, v6
	v_add_u32_e32 v16, v16, v7
	v_add_u32_e32 v16, v16, v8
	v_add_u32_e32 v16, v16, v9
	v_add_u32_e32 v16, v16, v10
	v_add_u32_e32 v16, v16, v11
	v_add_u32_e32 v16, v16, v12
	v_add_u32_e32 v16, v16, v13
	v_add_u32_e32 v16, v16, v14
	v_add_u32_e32 v16, v16, v15
	v_cmp_eq_u32_e32 vcc, s29, v16
	s_cbranch_vccnz .LBB0_19
	s_and_b32 s2, s9, 0xff
	s_cmp_eq_u32 s2, 0
	s_mov_b64 s[2:3], -1
	s_mov_b64 s[6:7], -1
	s_sleep 1
	s_cbranch_scc1 .LBB0_24
	s_and_b64 vcc, exec, s[6:7]
	s_cbranch_vccz .LBB0_19
